# deferred weight conversion: converted bf16 tiles written with the nt policy
# baseline (speedup 1.0000x reference)
.LBB0_408:
	s_nop 0
	v_ashrrev_i32_e32 v136, 31, v0
	v_mul_lo_u32 v138, s61, v0
	v_mul_lo_u32 v139, s60, v136
	v_mad_u64_u32 v[136:137], s[0:1], s60, v0, 0
	v_add3_u32 v137, v137, v139, v138
	v_lshl_add_u64 v[136:137], v[136:137], 1, s[6:7]
	v_cvt_pk_bf16_f32 v132, v9, v5
	v_cvt_pk_bf16_f32 v133, v33, v29
	v_cvt_pk_bf16_f32 v134, v65, v61
	v_cvt_pk_bf16_f32 v135, v97, v93
	v_lshl_add_u64 v[130:131], v[130:131], 1, v[136:137]
	global_store_dwordx4 v[130:131], v[132:135], off nt

.LBB0_508:
	v_mul_hi_i32_i24_e32 v153, s50, v0
	v_mul_i32_i24_e32 v152, s50, v0
	v_lshl_add_u64 v[152:153], v[152:153], 1, s[48:49]
	s_waitcnt vmcnt(6)
	v_cvt_pk_bf16_f32 v138, v22, v18
	s_waitcnt vmcnt(4)
	v_cvt_pk_bf16_f32 v139, v54, v50
	s_waitcnt vmcnt(2)
	v_cvt_pk_bf16_f32 v140, v86, v82
	s_waitcnt vmcnt(0)
	v_cvt_pk_bf16_f32 v141, v118, v114
	v_lshl_add_u64 v[152:153], v[136:137], 1, v[152:153]
	s_and_b64 vcc, exec, s[42:43]
	v_or_b32_e32 v0, 1, v149
	global_store_dwordx4 v[152:153], v[138:141], off nt
	s_cbranch_vccnz .LBB0_514
	s_movk_i32 s12, 0xffe
	v_cmp_lt_u32_e32 vcc, s12, v149
	v_lshlrev_b32_e32 v135, 1, v0
	s_and_saveexec_b64 s[12:13], vcc
	s_xor_b64 s[12:13], exec, s[12:13]
	s_and_b32 s26, s85, 0xffe0
	s_cmpk_eq_i32 s26, 0x60
	s_cselect_b64 vcc, -1, 0
	s_and_b32 s26, s84, 0x1f80
	s_and_b32 s27, s85, 1
	v_and_b32_e32 v135, 0x7a, v135
	s_or_b32 s26, s26, s27
	v_or_b32_e32 v135, s26, v135
	v_cndmask_b32_e32 v0, v0, v135, vcc
	s_andn2_saveexec_b64 s[12:13], s[12:13]
	v_and_b32_e32 v0, 58, v135
	v_or3_b32 v0, v145, v0, s84
	s_or_b64 exec, exec, s[12:13]
.LBB0_514:
	v_ashrrev_i32_e32 v135, 31, v0
	v_mul_lo_u32 v154, s51, v0
	v_mul_lo_u32 v135, s50, v135
	v_mad_u64_u32 v[152:153], s[12:13], s50, v0, 0
	v_add3_u32 v153, v153, v135, v154
	v_lshl_add_u64 v[152:153], v[152:153], 1, s[48:49]
	v_cvt_pk_bf16_f32 v138, v23, v19
	v_cvt_pk_bf16_f32 v139, v55, v51
	v_cvt_pk_bf16_f32 v140, v87, v83
	v_cvt_pk_bf16_f32 v141, v119, v115
	v_lshl_add_u64 v[152:153], v[136:137], 1, v[152:153]
	s_and_b64 vcc, exec, s[42:43]
	v_or_b32_e32 v0, 2, v149
	global_store_dwordx4 v[152:153], v[138:141], off nt
	s_cbranch_vccnz .LBB0_520
	s_movk_i32 s12, 0xffd
	v_cmp_lt_u32_e32 vcc, s12, v149
	v_lshlrev_b32_e32 v135, 1, v0
	s_and_saveexec_b64 s[12:13], vcc
	s_xor_b64 s[12:13], exec, s[12:13]
	s_and_b32 s26, s85, 0xffe0
	s_cmpk_eq_i32 s26, 0x60
	s_cselect_b64 vcc, -1, 0
	s_and_b32 s26, s84, 0x1f80
	s_and_b32 s27, s85, 1
	v_and_b32_e32 v135, 0x7c, v135
	s_or_b32 s26, s26, s27
	v_or_b32_e32 v135, s26, v135
	v_cndmask_b32_e32 v0, v0, v135, vcc
	s_andn2_saveexec_b64 s[12:13], s[12:13]
	v_and_b32_e32 v0, 60, v135
	v_or3_b32 v0, v145, v0, s84
	s_or_b64 exec, exec, s[12:13]
.LBB0_520:
	v_ashrrev_i32_e32 v135, 31, v0
	v_mul_lo_u32 v154, s51, v0
	v_mul_lo_u32 v135, s50, v135
	v_mad_u64_u32 v[152:153], s[12:13], s50, v0, 0
	v_add3_u32 v153, v153, v135, v154
	v_lshl_add_u64 v[152:153], v[152:153], 1, s[48:49]
	v_cvt_pk_bf16_f32 v138, v24, v20
	v_cvt_pk_bf16_f32 v139, v56, v52
	v_cvt_pk_bf16_f32 v140, v88, v84
	v_cvt_pk_bf16_f32 v141, v120, v116
	v_lshl_add_u64 v[152:153], v[136:137], 1, v[152:153]
	s_and_b64 vcc, exec, s[42:43]
	v_or_b32_e32 v0, 3, v149
	global_store_dwordx4 v[152:153], v[138:141], off nt
	s_cbranch_vccnz .LBB0_526
	s_movk_i32 s12, 0xffc
	v_cmp_lt_u32_e32 vcc, s12, v149
	v_lshlrev_b32_e32 v135, 1, v0
	s_and_saveexec_b64 s[12:13], vcc
	s_xor_b64 s[12:13], exec, s[12:13]
	s_and_b32 s26, s85, 0xffe0
	s_cmpk_eq_i32 s26, 0x60
	s_cselect_b64 vcc, -1, 0
	s_and_b32 s26, s84, 0x1f80
	s_and_b32 s27, s85, 1
	v_and_b32_e32 v135, 0x7e, v135
	s_or_b32 s26, s26, s27
	v_or_b32_e32 v135, s26, v135
	v_cndmask_b32_e32 v0, v0, v135, vcc
	s_andn2_saveexec_b64 s[12:13], s[12:13]
	v_and_b32_e32 v0, 62, v135
	v_or3_b32 v0, v145, v0, s84
	s_or_b64 exec, exec, s[12:13]
.LBB0_526:
	v_ashrrev_i32_e32 v135, 31, v0
	v_mul_lo_u32 v149, s51, v0
	v_mul_lo_u32 v135, s50, v135
	v_mad_u64_u32 v[152:153], s[12:13], s50, v0, 0
	v_add3_u32 v153, v153, v135, v149
	v_lshl_add_u64 v[152:153], v[152:153], 1, s[48:49]
	v_cvt_pk_bf16_f32 v138, v25, v21
	v_cvt_pk_bf16_f32 v139, v57, v53
	v_cvt_pk_bf16_f32 v140, v89, v85
	v_cvt_pk_bf16_f32 v141, v121, v117
	v_lshl_add_u64 v[136:137], v[136:137], 1, v[152:153]
	global_store_dwordx4 v[136:137], v[138:141], off nt
	s_or_b64 exec, exec, s[8:9]
	s_and_saveexec_b64 s[8:9], s[38:39]
	s_cbranch_execnz .LBB0_554

.LBB0_534:
	v_mul_hi_i32_i24_e32 v139, s26, v0
	v_mul_i32_i24_e32 v138, s26, v0
	v_lshl_add_u64 v[138:139], v[138:139], 1, s[8:9]
	s_waitcnt vmcnt(6)
	v_cvt_pk_bf16_f32 v160, v38, v34
	s_waitcnt vmcnt(4)
	v_cvt_pk_bf16_f32 v161, v70, v66
	s_waitcnt vmcnt(2)
	v_cvt_pk_bf16_f32 v162, v102, v98
	s_waitcnt vmcnt(0)
	v_cvt_pk_bf16_f32 v163, v126, v122
	v_lshl_add_u64 v[138:139], v[140:141], 1, v[138:139]
	s_and_b64 vcc, exec, s[44:45]
	v_or_b32_e32 v0, 1, v152
	global_store_dwordx4 v[138:139], v[160:163], off nt
	s_cbranch_vccnz .LBB0_540
	s_movk_i32 s64, 0xffe
	v_cmp_lt_u32_e32 vcc, s64, v152
	v_lshlrev_b32_e32 v135, 1, v0
	s_and_saveexec_b64 s[64:65], vcc
	s_xor_b64 s[64:65], exec, s[64:65]
	s_and_b32 s68, s88, 0x7fe0
	s_cmpk_eq_i32 s68, 0x60
	s_cselect_b64 vcc, -1, 0
	s_and_b32 s68, s87, 0x1f80
	s_and_b32 s69, s88, 1
	v_and_b32_e32 v135, 0x7a, v135
	s_or_b32 s68, s68, s69
	v_or_b32_e32 v135, s68, v135
	v_cndmask_b32_e32 v0, v0, v135, vcc
	s_andn2_saveexec_b64 s[64:65], s[64:65]
	v_and_b32_e32 v0, 58, v135
	v_or3_b32 v0, v145, v0, s87
	s_or_b64 exec, exec, s[64:65]
.LBB0_540:
	v_ashrrev_i32_e32 v135, 31, v0
	v_mul_lo_u32 v153, s27, v0
	v_mul_lo_u32 v135, s26, v135
	v_mad_u64_u32 v[138:139], s[64:65], s26, v0, 0
	v_add3_u32 v139, v139, v135, v153
	v_lshl_add_u64 v[138:139], v[138:139], 1, s[8:9]
	v_cvt_pk_bf16_f32 v160, v39, v35
	v_cvt_pk_bf16_f32 v161, v71, v67
	v_cvt_pk_bf16_f32 v162, v103, v99
	v_cvt_pk_bf16_f32 v163, v127, v123
	v_lshl_add_u64 v[138:139], v[140:141], 1, v[138:139]
	s_and_b64 vcc, exec, s[44:45]
	v_or_b32_e32 v0, 2, v152
	global_store_dwordx4 v[138:139], v[160:163], off nt
	s_cbranch_vccnz .LBB0_546
	s_movk_i32 s64, 0xffd
	v_cmp_lt_u32_e32 vcc, s64, v152
	v_lshlrev_b32_e32 v135, 1, v0
	s_and_saveexec_b64 s[64:65], vcc
	s_xor_b64 s[64:65], exec, s[64:65]
	s_and_b32 s68, s88, 0x7fe0
	s_cmpk_eq_i32 s68, 0x60
	s_cselect_b64 vcc, -1, 0
	s_and_b32 s68, s87, 0x1f80
	s_and_b32 s69, s88, 1
	v_and_b32_e32 v135, 0x7c, v135
	s_or_b32 s68, s68, s69
	v_or_b32_e32 v135, s68, v135
	v_cndmask_b32_e32 v0, v0, v135, vcc
	s_andn2_saveexec_b64 s[64:65], s[64:65]
	v_and_b32_e32 v0, 60, v135
	v_or3_b32 v0, v145, v0, s87
	s_or_b64 exec, exec, s[64:65]
.LBB0_546:
	v_ashrrev_i32_e32 v135, 31, v0
	v_mul_lo_u32 v153, s27, v0
	v_mul_lo_u32 v135, s26, v135
	v_mad_u64_u32 v[138:139], s[64:65], s26, v0, 0
	v_add3_u32 v139, v139, v135, v153
	v_lshl_add_u64 v[138:139], v[138:139], 1, s[8:9]
	v_cvt_pk_bf16_f32 v160, v40, v36
	v_cvt_pk_bf16_f32 v161, v72, v68
	v_cvt_pk_bf16_f32 v162, v104, v100
	v_cvt_pk_bf16_f32 v163, v128, v124
	v_lshl_add_u64 v[138:139], v[140:141], 1, v[138:139]
	s_and_b64 vcc, exec, s[44:45]
	v_or_b32_e32 v0, 3, v152
	global_store_dwordx4 v[138:139], v[160:163], off nt
	s_cbranch_vccnz .LBB0_552
	s_movk_i32 s44, 0xffc
	v_cmp_lt_u32_e32 vcc, s44, v152
	v_lshlrev_b32_e32 v135, 1, v0
	s_and_saveexec_b64 s[44:45], vcc
	s_xor_b64 s[44:45], exec, s[44:45]
	s_and_b32 s64, s88, 0x7fe0
	s_cmpk_eq_i32 s64, 0x60
	s_cselect_b64 vcc, -1, 0
	s_and_b32 s64, s87, 0x1f80
	s_and_b32 s65, s88, 1
	v_and_b32_e32 v135, 0x7e, v135
	s_or_b32 s64, s64, s65
	v_or_b32_e32 v135, s64, v135
	v_cndmask_b32_e32 v0, v0, v135, vcc
	s_andn2_saveexec_b64 s[44:45], s[44:45]
	v_and_b32_e32 v0, 62, v135
	v_or3_b32 v0, v145, v0, s87
	s_or_b64 exec, exec, s[44:45]
.LBB0_552:
	v_ashrrev_i32_e32 v135, 31, v0
	v_mul_lo_u32 v158, s27, v0
	v_mul_lo_u32 v135, s26, v135
	v_mad_u64_u32 v[138:139], s[26:27], s26, v0, 0
	v_add3_u32 v139, v139, v135, v158
	v_lshl_add_u64 v[138:139], v[138:139], 1, s[8:9]
	v_cvt_pk_bf16_f32 v152, v41, v37
	v_cvt_pk_bf16_f32 v153, v73, v69
	v_cvt_pk_bf16_f32 v154, v105, v101
	v_cvt_pk_bf16_f32 v155, v129, v125
	v_lshl_add_u64 v[138:139], v[140:141], 1, v[138:139]
	global_store_dwordx4 v[138:139], v[152:155], off nt
	s_or_b64 exec, exec, s[66:67]
	s_and_saveexec_b64 s[8:9], s[42:43]
	s_cbranch_execnz .LBB0_503

.LBB0_559:
	v_mul_hi_i32_i24_e32 v141, s40, v0
	v_mul_i32_i24_e32 v140, s40, v0
	v_lshl_add_u64 v[140:141], v[140:141], 1, s[52:53]
	s_waitcnt vmcnt(6)
	v_cvt_pk_bf16_f32 v136, v14, v10
	s_waitcnt vmcnt(4)
	v_cvt_pk_bf16_f32 v137, v46, v42
	s_waitcnt vmcnt(2)
	v_cvt_pk_bf16_f32 v138, v78, v74
	s_waitcnt vmcnt(0)
	v_cvt_pk_bf16_f32 v139, v110, v106
	v_lshl_add_u64 v[140:141], v[132:133], 1, v[140:141]
	s_and_b64 vcc, exec, s[38:39]
	v_or_b32_e32 v0, 1, v147
	global_store_dwordx4 v[140:141], v[136:139], off nt
	s_cbranch_vccnz .LBB0_565
	s_movk_i32 s12, 0xffe
	v_cmp_lt_u32_e32 vcc, s12, v147
	v_lshlrev_b32_e32 v135, 1, v0
	s_and_saveexec_b64 s[12:13], vcc
	s_xor_b64 s[12:13], exec, s[12:13]
	s_and_b32 s22, s83, 0x7fe0
	s_cmpk_eq_i32 s22, 0x60
	s_cselect_b64 vcc, -1, 0
	s_and_b32 s22, s80, 0x1f80
	s_and_b32 s23, s83, 1
	v_and_b32_e32 v135, 0x7a, v135
	s_or_b32 s22, s22, s23
	v_or_b32_e32 v135, s22, v135
	v_cndmask_b32_e32 v0, v0, v135, vcc
	s_andn2_saveexec_b64 s[12:13], s[12:13]
	v_and_b32_e32 v0, 58, v135
	v_or3_b32 v0, v145, v0, s80
	s_or_b64 exec, exec, s[12:13]
.LBB0_565:
	v_ashrrev_i32_e32 v135, 31, v0
	v_mul_lo_u32 v149, s41, v0
	v_mul_lo_u32 v135, s40, v135
	v_mad_u64_u32 v[140:141], s[12:13], s40, v0, 0
	v_add3_u32 v141, v141, v135, v149
	v_lshl_add_u64 v[140:141], v[140:141], 1, s[52:53]
	v_cvt_pk_bf16_f32 v136, v15, v11
	v_cvt_pk_bf16_f32 v137, v47, v43
	v_cvt_pk_bf16_f32 v138, v79, v75
	v_cvt_pk_bf16_f32 v139, v111, v107
	v_lshl_add_u64 v[140:141], v[132:133], 1, v[140:141]
	s_and_b64 vcc, exec, s[38:39]
	v_or_b32_e32 v0, 2, v147
	global_store_dwordx4 v[140:141], v[136:139], off nt
	s_cbranch_vccnz .LBB0_571
	s_movk_i32 s12, 0xffd
	v_cmp_lt_u32_e32 vcc, s12, v147
	v_lshlrev_b32_e32 v135, 1, v0
	s_and_saveexec_b64 s[12:13], vcc
	s_xor_b64 s[12:13], exec, s[12:13]
	s_and_b32 s22, s83, 0x7fe0
	s_cmpk_eq_i32 s22, 0x60
	s_cselect_b64 vcc, -1, 0
	s_and_b32 s22, s80, 0x1f80
	s_and_b32 s23, s83, 1
	v_and_b32_e32 v135, 0x7c, v135
	s_or_b32 s22, s22, s23
	v_or_b32_e32 v135, s22, v135
	v_cndmask_b32_e32 v0, v0, v135, vcc
	s_andn2_saveexec_b64 s[12:13], s[12:13]
	v_and_b32_e32 v0, 60, v135
	v_or3_b32 v0, v145, v0, s80
	s_or_b64 exec, exec, s[12:13]
.LBB0_571:
	v_ashrrev_i32_e32 v135, 31, v0
	v_mul_lo_u32 v149, s41, v0
	v_mul_lo_u32 v135, s40, v135
	v_mad_u64_u32 v[140:141], s[12:13], s40, v0, 0
	v_add3_u32 v141, v141, v135, v149
	v_lshl_add_u64 v[140:141], v[140:141], 1, s[52:53]
	v_cvt_pk_bf16_f32 v136, v16, v12
	v_cvt_pk_bf16_f32 v137, v48, v44
	v_cvt_pk_bf16_f32 v138, v80, v76
	v_cvt_pk_bf16_f32 v139, v112, v108
	v_lshl_add_u64 v[140:141], v[132:133], 1, v[140:141]
	s_and_b64 vcc, exec, s[38:39]
	v_or_b32_e32 v0, 3, v147
	global_store_dwordx4 v[140:141], v[136:139], off nt
	s_cbranch_vccnz .LBB0_577
	s_movk_i32 s12, 0xffc
	v_cmp_lt_u32_e32 vcc, s12, v147
	v_lshlrev_b32_e32 v135, 1, v0
	s_and_saveexec_b64 s[12:13], vcc
	s_xor_b64 s[12:13], exec, s[12:13]
	s_and_b32 s22, s83, 0x7fe0
	s_cmpk_eq_i32 s22, 0x60
	s_cselect_b64 vcc, -1, 0
	s_and_b32 s22, s80, 0x1f80
	s_and_b32 s23, s83, 1
	v_and_b32_e32 v135, 0x7e, v135
	s_or_b32 s22, s22, s23
	v_or_b32_e32 v135, s22, v135
	v_cndmask_b32_e32 v0, v0, v135, vcc
	s_andn2_saveexec_b64 s[12:13], s[12:13]
	v_and_b32_e32 v0, 62, v135
	v_or3_b32 v0, v145, v0, s80
	s_or_b64 exec, exec, s[12:13]
.LBB0_577:
	v_ashrrev_i32_e32 v135, 31, v0
	v_mul_lo_u32 v147, s41, v0
	v_mul_lo_u32 v135, s40, v135
	v_mad_u64_u32 v[140:141], s[12:13], s40, v0, 0
	v_add3_u32 v141, v141, v135, v147
	v_lshl_add_u64 v[140:141], v[140:141], 1, s[52:53]
	v_cvt_pk_bf16_f32 v136, v17, v13
	v_cvt_pk_bf16_f32 v137, v49, v45
	v_cvt_pk_bf16_f32 v138, v81, v77
	v_cvt_pk_bf16_f32 v139, v113, v109
	v_lshl_add_u64 v[132:133], v[132:133], 1, v[140:141]
	global_store_dwordx4 v[132:133], v[136:139], off nt
	s_or_b64 exec, exec, s[8:9]
	s_and_saveexec_b64 s[8:9], s[0:1]
	s_cbranch_execz .LBB0_409

.LBB0_583:
	v_mul_hi_i32_i24_e32 v133, s60, v0
	v_mul_i32_i24_e32 v132, s60, v0
	v_lshl_add_u64 v[132:133], v[132:133], 1, s[6:7]
	s_waitcnt vmcnt(6)
	v_cvt_pk_bf16_f32 v136, v6, v2
	s_waitcnt vmcnt(4)
	v_cvt_pk_bf16_f32 v137, v30, v26
	s_waitcnt vmcnt(2)
	v_cvt_pk_bf16_f32 v138, v62, v58
	s_waitcnt vmcnt(0)
	v_cvt_pk_bf16_f32 v139, v94, v90
	v_lshl_add_u64 v[132:133], v[130:131], 1, v[132:133]
	s_and_b64 vcc, exec, s[0:1]
	v_or_b32_e32 v0, 1, v134
	global_store_dwordx4 v[132:133], v[136:139], off nt
	s_cbranch_vccnz .LBB0_589
	s_movk_i32 s12, 0xffe
	v_cmp_lt_u32_e32 vcc, s12, v134
	v_lshlrev_b32_e32 v132, 1, v0
	s_and_saveexec_b64 s[12:13], vcc
	s_xor_b64 s[12:13], exec, s[12:13]
	s_and_b32 s22, s79, 0x7fe0
	s_cmpk_eq_i32 s22, 0x60
	s_cselect_b64 vcc, -1, 0
	s_and_b32 s22, s14, 0x1f80
	s_and_b32 s23, s79, 1
	v_and_b32_e32 v132, 0x7a, v132
	s_or_b32 s22, s22, s23
	v_or_b32_e32 v132, s22, v132
	v_cndmask_b32_e32 v0, v0, v132, vcc
	s_andn2_saveexec_b64 s[12:13], s[12:13]
	v_and_b32_e32 v0, 58, v132
	v_or3_b32 v0, v145, v0, s14
	s_or_b64 exec, exec, s[12:13]
.LBB0_589:
	v_ashrrev_i32_e32 v132, 31, v0
	v_mul_lo_u32 v135, s61, v0
	v_mul_lo_u32 v140, s60, v132
	v_mad_u64_u32 v[132:133], s[12:13], s60, v0, 0
	v_add3_u32 v133, v133, v140, v135
	v_lshl_add_u64 v[132:133], v[132:133], 1, s[6:7]
	v_cvt_pk_bf16_f32 v136, v7, v3
	v_cvt_pk_bf16_f32 v137, v31, v27
	v_cvt_pk_bf16_f32 v138, v63, v59
	v_cvt_pk_bf16_f32 v139, v95, v91
	v_lshl_add_u64 v[132:133], v[130:131], 1, v[132:133]
	s_and_b64 vcc, exec, s[0:1]
	v_or_b32_e32 v0, 2, v134
	global_store_dwordx4 v[132:133], v[136:139], off nt
	s_cbranch_vccnz .LBB0_595
	s_movk_i32 s12, 0xffd
	v_cmp_lt_u32_e32 vcc, s12, v134
	v_lshlrev_b32_e32 v132, 1, v0
	s_and_saveexec_b64 s[12:13], vcc
	s_xor_b64 s[12:13], exec, s[12:13]
	s_and_b32 s22, s79, 0x7fe0
	s_cmpk_eq_i32 s22, 0x60
	s_cselect_b64 vcc, -1, 0
	s_and_b32 s22, s14, 0x1f80
	s_and_b32 s23, s79, 1
	v_and_b32_e32 v132, 0x7c, v132
	s_or_b32 s22, s22, s23
	v_or_b32_e32 v132, s22, v132
	v_cndmask_b32_e32 v0, v0, v132, vcc
	s_andn2_saveexec_b64 s[12:13], s[12:13]
	v_and_b32_e32 v0, 60, v132
	v_or3_b32 v0, v145, v0, s14
	s_or_b64 exec, exec, s[12:13]
.LBB0_595:
	v_ashrrev_i32_e32 v132, 31, v0
	v_mul_lo_u32 v135, s61, v0
	v_mul_lo_u32 v140, s60, v132
	v_mad_u64_u32 v[132:133], s[12:13], s60, v0, 0
	v_add3_u32 v133, v133, v140, v135
	v_lshl_add_u64 v[132:133], v[132:133], 1, s[6:7]
	v_cvt_pk_bf16_f32 v136, v8, v4
	v_cvt_pk_bf16_f32 v137, v32, v28
	v_cvt_pk_bf16_f32 v138, v64, v60
	v_cvt_pk_bf16_f32 v139, v96, v92
	v_lshl_add_u64 v[132:133], v[130:131], 1, v[132:133]
	s_and_b64 vcc, exec, s[0:1]
	v_or_b32_e32 v0, 3, v134
	global_store_dwordx4 v[132:133], v[136:139], off nt
	s_cbranch_vccnz .LBB0_408
	s_movk_i32 s0, 0xffc
	v_cmp_lt_u32_e32 vcc, s0, v134
	v_lshlrev_b32_e32 v132, 1, v0
	s_and_saveexec_b64 s[0:1], vcc
	s_xor_b64 s[0:1], exec, s[0:1]
	s_and_b32 s12, s79, 0x7fe0
	s_cmpk_eq_i32 s12, 0x60
	s_cselect_b64 vcc, -1, 0
	s_and_b32 s12, s14, 0x1f80
	s_and_b32 s13, s79, 1
	v_and_b32_e32 v132, 0x7e, v132
	s_or_b32 s12, s12, s13
	v_or_b32_e32 v132, s12, v132
	v_cndmask_b32_e32 v0, v0, v132, vcc
	s_andn2_saveexec_b64 s[0:1], s[0:1]
	s_cbranch_execz .LBB0_407
	v_and_b32_e32 v0, 62, v132
	v_or3_b32 v0, v145, v0, s14
	s_branch .LBB0_407
